# v20 plus the last remaining row-phase wave_sum butterfly converted to DPP + permlane32_swap
# baseline (speedup 1.0000x reference)
; #define GAS __attribute__((address_space(1)))
; __device__ __forceinline__ float bflo(unsigned u) { return __uint_as_float(u << 16); }
; __device__ __forceinline__ float bfhi(unsigned u) { return __uint_as_float(u & 0xffff0000u); }
; __device__ __forceinline__ float wave_sum(float v) {
; #pragma unroll
;     for (int o = 1; o < 64; o <<= 1) v += __shfl_xor(v, o);
;     return v;
; }
; template <bool XIN_BF, bool XOUT_BF>
; __device__ __forceinline__ void rows_update_g(const Ctx& C, const float* xin, const bf16* xin_bf, const bf16* Y, const float* wpost, float scale, float* xout, bf16* xout_bf, const float* wpre, bf16* HN) {
;     const int gw = C.bid * NWAVES + C.wave, NGW = C.G * NWAVES;
;     for (int m = gw; m < T; m += NGW) {
;         const GAS v2u* yr = (const GAS v2u*)(Y + (size_t)m * D) + C.lane;
;         f32x4 v[8]; float s = 0.f;
; #pragma unroll
;         for (int j = 0; j < 8; ++j) { const v2u w = yr[64 * j]; v[j] = (f32x4){bflo(w.x), bfhi(w.x), bflo(w.y), bfhi(w.y)}; s += (v[j].x * v[j].x + v[j].y * v[j].y) + (v[j].z * v[j].z + v[j].w * v[j].w); }
;         const float rstd = scale / sqrtf(wave_sum(s) * (1.0f / D) + EPS);
.LBB0_1075:
	v_lshl_add_u64 v[22:23], s[0:1], 0, v[0:1]
	v_add_co_u32_e32 v24, vcc, 0xa100000, v22
	s_nop 1
	v_addc_co_u32_e32 v25, vcc, 0, v23, vcc
	global_load_dwordx2 v[26:27], v[24:25], off
	global_load_dwordx2 v[28:29], v[24:25], off offset:512
	global_load_dwordx2 v[30:31], v[24:25], off offset:1024
	global_load_dwordx2 v[32:33], v[24:25], off offset:1536
	global_load_dwordx2 v[34:35], v[24:25], off offset:2048
	global_load_dwordx2 v[36:37], v[24:25], off offset:2560
	global_load_dwordx2 v[40:41], v[24:25], off offset:3072
	global_load_dwordx2 v[46:47], v[24:25], off offset:3584
	global_load_dwordx4 v[42:45], v[2:3], off
	v_lshl_add_u64 v[24:25], s[10:11], 0, v[0:1]
	global_load_dwordx2 v[48:49], v[24:25], off
	s_waitcnt vmcnt(9)
	v_and_b32_e32 v51, 0xffff0000, v26
	v_and_b32_e32 v61, 0xffff0000, v27
	v_lshlrev_b32_e32 v50, 16, v26
	v_lshlrev_b32_e32 v60, 16, v27
	s_waitcnt vmcnt(8)
	v_lshlrev_b32_e32 v63, 16, v29
	v_lshlrev_b32_e32 v62, 16, v28
	v_and_b32_e32 v65, 0xffff0000, v29
	v_and_b32_e32 v64, 0xffff0000, v28
	s_waitcnt vmcnt(7)
	v_lshlrev_b32_e32 v66, 16, v30
	v_and_b32_e32 v67, 0xffff0000, v30
	v_lshlrev_b32_e32 v68, 16, v31
	v_and_b32_e32 v69, 0xffff0000, v31
	s_waitcnt vmcnt(6)
	v_lshlrev_b32_e32 v71, 16, v32
	s_waitcnt vmcnt(2)
	v_lshlrev_b32_e32 v31, 16, v46
	v_and_b32_e32 v29, 0xffff0000, v46
	v_mul_f32_e32 v28, v61, v61
	v_mul_f32_e32 v30, v51, v51
	v_and_b32_e32 v73, 0xffff0000, v32
	v_lshlrev_b32_e32 v74, 16, v33
	v_and_b32_e32 v75, 0xffff0000, v33
	v_lshlrev_b32_e32 v77, 16, v35
	v_lshlrev_b32_e32 v76, 16, v34
	v_and_b32_e32 v79, 0xffff0000, v35
	v_and_b32_e32 v78, 0xffff0000, v34
	v_lshlrev_b32_e32 v32, 16, v40
	v_and_b32_e32 v33, 0xffff0000, v40
	v_lshlrev_b32_e32 v34, 16, v41
	v_and_b32_e32 v35, 0xffff0000, v41
	v_lshlrev_b32_e32 v26, 16, v47
	v_and_b32_e32 v27, 0xffff0000, v47
	v_pk_mul_f32 v[40:41], v[64:65], v[64:65]
	v_mov_b32_e32 v47, v71
	v_mul_f32_e32 v46, v67, v67
	v_mul_f32_e32 v70, v69, v69
	v_pk_fma_f32 v[86:87], v[60:61], v[60:61], v[28:29] op_sel_hi:[1,1,0]
	v_pk_fma_f32 v[88:89], v[50:51], v[50:51], v[30:31] op_sel_hi:[1,1,0]
	v_pk_fma_f32 v[40:41], v[62:63], v[62:63], v[40:41]
	v_pk_fma_f32 v[90:91], v[66:67], v[66:67], v[46:47] op_sel_hi:[1,1,0]
	v_pk_fma_f32 v[92:93], v[68:69], v[68:69], v[70:71] op_sel_hi:[1,1,0]
	v_mov_b32_e32 v70, v88
	v_mov_b32_e32 v46, v86
	v_mul_f32_e32 v84, v73, v73
	v_mul_f32_e32 v96, v74, v74
	v_mul_f32_e32 v97, v75, v75
	v_pk_add_f32 v[86:87], v[88:89], v[86:87]
	v_pk_add_f32 v[40:41], v[40:41], v[40:41] op_sel:[0,1] op_sel_hi:[1,0]
	v_pk_mul_f32 v[46:47], v[70:71], v[46:47]
	v_mov_b32_e32 v91, v96
	v_mov_b32_e32 v93, v97
	v_mov_b32_e32 v41, v84
	v_mov_b32_e32 v87, v47
	v_pk_mul_f32 v[80:81], v[78:79], v[78:79]
	v_pk_add_f32 v[88:89], v[90:91], v[92:93]
	v_pk_add_f32 v[40:41], v[86:87], v[40:41]
	v_pk_fma_f32 v[80:81], v[76:77], v[76:77], v[80:81]
	v_pk_add_f32 v[40:41], v[40:41], v[88:89]
	v_lshlrev_b32_e32 v39, 16, v37
	v_lshlrev_b32_e32 v38, 16, v36
	v_and_b32_e32 v37, 0xffff0000, v37
	v_and_b32_e32 v36, 0xffff0000, v36
	v_pk_add_f32 v[80:81], v[80:81], v[80:81] op_sel:[0,1] op_sel_hi:[1,0]
	v_pk_add_f32 v[40:41], v[40:41], v[40:41] op_sel:[0,1] op_sel_hi:[1,0]
	v_pk_mul_f32 v[82:83], v[36:37], v[36:37]
	v_mov_b32_e32 v85, v31
	v_mov_b32_e32 v84, v80
	v_mov_b32_e32 v30, v40
	v_mul_f32_e32 v72, v33, v33
	v_pk_fma_f32 v[82:83], v[38:39], v[38:39], v[82:83]
	v_pk_add_f32 v[40:41], v[40:41], v[80:81]
	v_pk_mul_f32 v[46:47], v[30:31], v[84:85]
	v_mul_f32_e32 v28, v35, v35
	v_mul_f32_e32 v98, v29, v29
	v_mul_f32_e32 v99, v26, v26
	v_mul_f32_e32 v100, v27, v27
	v_pk_fma_f32 v[94:95], v[32:33], v[32:33], v[72:73] op_sel_hi:[1,1,0]
	v_pk_add_f32 v[82:83], v[82:83], v[82:83] op_sel:[0,1] op_sel_hi:[1,0]
	v_mov_b32_e32 v41, v47
	v_pk_fma_f32 v[46:47], v[34:35], v[34:35], v[28:29] op_sel_hi:[1,1,0]
	v_mov_b32_e32 v95, v99
	v_mov_b32_e32 v83, v98
	v_mov_b32_e32 v47, v100
	v_pk_add_f32 v[40:41], v[40:41], v[82:83]
	v_pk_add_f32 v[46:47], v[94:95], v[46:47]
	s_nop 0
	v_pk_add_f32 v[40:41], v[40:41], v[46:47]
	s_waitcnt vmcnt(0)
	v_lshlrev_b32_e32 v46, 16, v48
	v_add_f32_e32 v28, v40, v41
	s_nop 1
	v_add_f32_dpp v28, v28, v28 quad_perm:[1,0,3,2] row_mask:0xf bank_mask:0xf
	v_add_co_u32_e32 v40, vcc, s12, v22
	v_and_b32_e32 v47, 0xffff0000, v48
	s_nop 0
	v_addc_co_u32_e32 v41, vcc, 0, v23, vcc
	s_nop 1
	v_add_f32_dpp v28, v28, v28 quad_perm:[2,3,0,1] row_mask:0xf bank_mask:0xf
	v_lshlrev_b32_e32 v48, 16, v49
	v_and_b32_e32 v49, 0xffff0000, v49
	s_nop 1
	v_add_f32_dpp v28, v28, v28 row_half_mirror row_mask:0xf bank_mask:0xf
	s_nop 1
	v_add_f32_dpp v28, v28, v28 row_mirror row_mask:0xf bank_mask:0xf
	ds_bpermute_b32 v30, v56, v28
	s_waitcnt lgkmcnt(0)
; #define GAS __attribute__((address_space(1)))
; __device__ __forceinline__ unsigned pk2(float lo, float hi) { f32x2_t v = {lo, hi}; bf16x2_t b = __builtin_convertvector(v, bf16x2_t); return __builtin_bit_cast(unsigned, b); }
; __device__ __forceinline__ float bflo(unsigned u) { return __uint_as_float(u << 16); }
; __device__ __forceinline__ float bfhi(unsigned u) { return __uint_as_float(u & 0xffff0000u); }
; __device__ __forceinline__ float wave_sum(float v) {
; #pragma unroll
;     for (int o = 1; o < 64; o <<= 1) v += __shfl_xor(v, o);
;     return v;
; }
; template <bool XIN_BF, bool XOUT_BF>
; __device__ __forceinline__ void rows_update_g(const Ctx& C, const float* xin, const bf16* xin_bf, const bf16* Y, const float* wpost, float scale, float* xout, bf16* xout_bf, const float* wpre, bf16* HN) {
;     ...
;         const float rstd = scale / sqrtf(wave_sum(s) * (1.0f / D) + EPS);
;         float s2 = 0.f;
; #pragma unroll
;         for (int j = 0; j < 8; ++j) { const f32x4 ww = *((const GAS f32x4*)wpost + C.lane + 64 * j); f32x4 xv;
;             if (XIN_BF) { const v2u xw = *((const GAS v2u*)(xin_bf + (size_t)m * D) + C.lane + 64 * j); xv = (f32x4){bflo(xw.x), bfhi(xw.x), bflo(xw.y), bfhi(xw.y)}; }
;             else xv = *((const GAS f32x4*)(xin + (size_t)m * D) + C.lane + 64 * j);
;             v[j] = xv + v[j] * rstd * ww;
;             if (XOUT_BF) { const v2u ow = (v2u){pk2(v[j].x, v[j].y), pk2(v[j].z, v[j].w)}; *((GAS v2u*)(xout_bf + (size_t)m * D) + C.lane + 64 * j) = ow;
;                 v[j] = (f32x4){bflo(ow.x), bfhi(ow.x), bflo(ow.y), bfhi(ow.y)}; }
;             else *((GAS f32x4*)(xout + (size_t)m * D) + C.lane + 64 * j) = v[j];
;             s2 += (v[j].x * v[j].x + v[j].y * v[j].y) + (v[j].z * v[j].z + v[j].w * v[j].w); }
	v_add_f32_e32 v28, v28, v30
	v_mov_b32_e32 v30, v28
	s_nop 1
	v_permlane32_swap_b32_e32 v30, v28
	v_add_f32_e32 v28, v28, v30
	v_fmamk_f32 v28, v28, 0x3a000000, v58
	v_mul_f32_e32 v30, 0x4f800000, v28
	v_cmp_gt_f32_e32 vcc, s3, v28
	s_nop 1
	v_cndmask_b32_e32 v28, v28, v30, vcc
	v_sqrt_f32_e32 v30, v28
	s_nop 0
	v_add_u32_e32 v70, -1, v30
	v_add_u32_e32 v72, 1, v30
	v_fma_f32 v80, -v70, v30, v28
	v_fma_f32 v81, -v72, v30, v28
	v_cmp_ge_f32_e64 s[6:7], 0, v80
	s_nop 1
	v_cndmask_b32_e64 v30, v30, v70, s[6:7]
	v_cmp_lt_f32_e64 s[6:7], 0, v81
	s_nop 1
	v_cndmask_b32_e64 v30, v30, v72, s[6:7]
	v_mul_f32_e32 v70, 0x37800000, v30
	v_cndmask_b32_e32 v30, v30, v70, vcc
	v_cmp_class_f32_e32 vcc, v28, v59
	s_nop 1
	v_cndmask_b32_e32 v28, v30, v28, vcc
	v_div_scale_f32 v30, s[6:7], v28, v28, 1.0
	v_rcp_f32_e32 v70, v30
	v_div_scale_f32 v72, vcc, 1.0, v28, 1.0
	v_fma_f32 v80, -v30, v70, 1.0
	v_fmac_f32_e32 v70, v80, v70
	v_mul_f32_e32 v80, v72, v70
	v_fma_f32 v81, -v30, v80, v72
	v_fmac_f32_e32 v80, v81, v70
	v_fma_f32 v30, -v30, v80, v72
	v_div_fmas_f32 v30, v30, v70, v80
	v_div_fixup_f32 v30, v30, v28, 1.0
	v_pk_mul_f32 v[50:51], v[30:31], v[50:51] op_sel_hi:[0,1]
	v_pk_mul_f32 v[60:61], v[30:31], v[60:61] op_sel_hi:[0,1]
	v_pk_fma_f32 v[44:45], v[44:45], v[60:61], v[48:49]
	v_pk_fma_f32 v[42:43], v[42:43], v[50:51], v[46:47]
	v_mov_b32_e32 v50, v62
	v_cvt_pk_bf16_f32 v42, v42, v43
	v_cvt_pk_bf16_f32 v43, v44, v45
	global_store_dwordx2 v[40:41], v[42:43], off
	global_load_dwordx2 v[48:49], v[24:25], off offset:512
	global_load_dwordx4 v[44:47], v[2:3], off offset:1024
	v_mov_b32_e32 v51, v64
	v_mov_b32_e32 v64, v63
	v_pk_mul_f32 v[50:51], v[30:31], v[50:51] op_sel_hi:[0,1]
	v_pk_mul_f32 v[60:61], v[30:31], v[64:65] op_sel_hi:[0,1]
	v_mov_b32_e32 v72, v71
	v_pk_mul_f32 v[32:33], v[30:31], v[32:33] op_sel_hi:[0,1]
	v_pk_mul_f32 v[34:35], v[30:31], v[34:35] op_sel_hi:[0,1]
	v_mov_b32_e32 v28, v31
	v_pk_mul_f32 v[26:27], v[26:27], v[30:31] op_sel_hi:[1,0]
	s_and_b64 vcc, exec, s[4:5]
	s_waitcnt vmcnt(1)
	v_lshlrev_b32_e32 v62, 16, v48
	v_and_b32_e32 v63, 0xffff0000, v48
	v_lshlrev_b32_e32 v48, 16, v49
	v_and_b32_e32 v49, 0xffff0000, v49
	s_waitcnt vmcnt(0)
	v_pk_fma_f32 v[46:47], v[46:47], v[60:61], v[48:49]
	v_pk_fma_f32 v[44:45], v[44:45], v[50:51], v[62:63]
	v_pk_mul_f32 v[60:61], v[30:31], v[66:67] op_sel_hi:[0,1]
	v_cvt_pk_bf16_f32 v44, v44, v45
	v_cvt_pk_bf16_f32 v45, v46, v47
	global_store_dwordx2 v[40:41], v[44:45], off offset:512
	global_load_dwordx2 v[50:51], v[24:25], off offset:1024
	global_load_dwordx4 v[46:49], v[2:3], off offset:2048
	v_pk_mul_f32 v[62:63], v[30:31], v[68:69] op_sel_hi:[0,1]
	s_waitcnt vmcnt(1)
	v_lshlrev_b32_e32 v64, 16, v50
	v_and_b32_e32 v65, 0xffff0000, v50
	v_lshlrev_b32_e32 v50, 16, v51
	v_and_b32_e32 v51, 0xffff0000, v51
	s_waitcnt vmcnt(0)
	v_pk_fma_f32 v[48:49], v[48:49], v[62:63], v[50:51]
	v_pk_fma_f32 v[46:47], v[46:47], v[60:61], v[64:65]
	v_pk_mul_f32 v[62:63], v[72:73], v[30:31] op_sel_hi:[1,0]
	v_cvt_pk_bf16_f32 v46, v46, v47
	v_cvt_pk_bf16_f32 v47, v48, v49
	global_store_dwordx2 v[40:41], v[46:47], off offset:1024
	global_load_dwordx2 v[60:61], v[24:25], off offset:1536
	global_load_dwordx4 v[48:51], v[2:3], off offset:3072
	v_pk_mul_f32 v[64:65], v[74:75], v[30:31] op_sel_hi:[1,0]
	s_waitcnt vmcnt(1)
	v_lshlrev_b32_e32 v66, 16, v60
	v_and_b32_e32 v67, 0xffff0000, v60
	v_lshlrev_b32_e32 v60, 16, v61
	v_and_b32_e32 v61, 0xffff0000, v61
	s_waitcnt vmcnt(0)
	v_pk_fma_f32 v[50:51], v[50:51], v[64:65], v[60:61]
	v_pk_fma_f32 v[48:49], v[48:49], v[62:63], v[66:67]
	v_mov_b32_e32 v64, v76
	v_cvt_pk_bf16_f32 v48, v48, v49
	v_cvt_pk_bf16_f32 v49, v50, v51
	global_store_dwordx2 v[40:41], v[48:49], off offset:1536
	global_load_dwordx2 v[50:51], v[24:25], off offset:2048
	global_load_dwordx4 v[60:63], v[4:5], off
	v_mov_b32_e32 v65, v78
	v_mov_b32_e32 v78, v77
	v_pk_mul_f32 v[64:65], v[30:31], v[64:65] op_sel_hi:[0,1]
	v_pk_mul_f32 v[66:67], v[30:31], v[78:79] op_sel_hi:[0,1]
	s_waitcnt vmcnt(1)
	v_lshlrev_b32_e32 v68, 16, v50
	v_and_b32_e32 v69, 0xffff0000, v50
	v_lshlrev_b32_e32 v50, 16, v51
	v_and_b32_e32 v51, 0xffff0000, v51
	s_waitcnt vmcnt(0)
	v_pk_fma_f32 v[62:63], v[62:63], v[66:67], v[50:51]
	v_pk_fma_f32 v[50:51], v[60:61], v[64:65], v[68:69]
	v_mov_b32_e32 v66, v38
	v_cvt_pk_bf16_f32 v50, v50, v51
	v_cvt_pk_bf16_f32 v51, v62, v63
	global_store_dwordx2 v[40:41], v[50:51], off offset:2048
	global_load_dwordx2 v[64:65], v[24:25], off offset:2560
	global_load_dwordx4 v[60:63], v[6:7], off
	v_mov_b32_e32 v67, v36
	v_mov_b32_e32 v36, v39
	v_pk_mul_f32 v[38:39], v[30:31], v[66:67] op_sel_hi:[0,1]
	v_pk_mul_f32 v[36:37], v[30:31], v[36:37] op_sel_hi:[0,1]
	s_waitcnt vmcnt(1)
	v_lshlrev_b32_e32 v66, 16, v64
	v_and_b32_e32 v67, 0xffff0000, v64
	v_lshlrev_b32_e32 v64, 16, v65
	v_and_b32_e32 v65, 0xffff0000, v65
	s_waitcnt vmcnt(0)
	v_pk_fma_f32 v[62:63], v[36:37], v[62:63], v[64:65]
	v_pk_fma_f32 v[36:37], v[38:39], v[60:61], v[66:67]
	s_nop 0
	v_cvt_pk_bf16_f32 v36, v36, v37
	v_cvt_pk_bf16_f32 v37, v62, v63
	global_store_dwordx2 v[40:41], v[36:37], off offset:2560
	global_load_dwordx2 v[38:39], v[24:25], off offset:3072
	global_load_dwordx4 v[60:63], v[8:9], off
	s_waitcnt vmcnt(1)
	v_lshlrev_b32_e32 v64, 16, v38
	v_and_b32_e32 v65, 0xffff0000, v38
	v_lshlrev_b32_e32 v38, 16, v39
	v_and_b32_e32 v39, 0xffff0000, v39
	s_waitcnt vmcnt(0)
	v_pk_fma_f32 v[34:35], v[34:35], v[62:63], v[38:39]
	v_pk_fma_f32 v[32:33], v[32:33], v[60:61], v[64:65]
	s_nop 0
	v_cvt_pk_bf16_f32 v32, v32, v33
	v_cvt_pk_bf16_f32 v33, v34, v35
	global_store_dwordx2 v[40:41], v[32:33], off offset:3072
	global_load_dwordx2 v[34:35], v[24:25], off offset:3584
	global_load_dwordx4 v[60:63], v[10:11], off
	v_pk_mul_f32 v[24:25], v[28:29], v[30:31] op_sel_hi:[1,0]
	s_waitcnt vmcnt(1)
	v_lshlrev_b32_e32 v28, 16, v34
	v_and_b32_e32 v29, 0xffff0000, v34
	v_lshlrev_b32_e32 v30, 16, v35
	v_and_b32_e32 v31, 0xffff0000, v35
	s_waitcnt vmcnt(0)
	v_pk_fma_f32 v[26:27], v[26:27], v[62:63], v[30:31]
	v_pk_fma_f32 v[24:25], v[24:25], v[60:61], v[28:29]
	s_nop 0
	v_cvt_pk_bf16_f32 v24, v24, v25
	v_cvt_pk_bf16_f32 v25, v26, v27
	global_store_dwordx2 v[40:41], v[24:25], off offset:3584
	s_cbranch_vccnz .LBB0_1074
; __device__ __forceinline__ float wave_sum(float v) {
; #pragma unroll
;     for (int o = 1; o < 64; o <<= 1) v += __shfl_xor(v, o);
;     return v;
; }
; template <bool XIN_BF, bool XOUT_BF>
; __device__ __forceinline__ void rows_update_g(const Ctx& C, const float* xin, const bf16* xin_bf, const bf16* Y, const float* wpost, float scale, float* xout, bf16* xout_bf, const float* wpre, bf16* HN) {
;     ...
;             s2 += (v[j].x * v[j].x + v[j].y * v[j].y) + (v[j].z * v[j].z + v[j].w * v[j].w); }
;         if (wpre) { const float r2 = 1.0f / sqrtf(wave_sum(s2) * (1.0f / D) + EPS);
	v_and_b32_e32 v39, 0xffff0000, v45
	v_and_b32_e32 v38, 0xffff0000, v44
	v_lshlrev_b32_e32 v35, 16, v45
	v_lshlrev_b32_e32 v34, 16, v44
	v_pk_mul_f32 v[26:27], v[38:39], v[38:39]
	v_lshlrev_b32_e32 v28, 16, v42
	v_and_b32_e32 v29, 0xffff0000, v42
	v_pk_fma_f32 v[26:27], v[34:35], v[34:35], v[26:27]
	v_lshlrev_b32_e32 v42, 16, v46
	v_and_b32_e32 v45, 0xffff0000, v46
	v_and_b32_e32 v44, s0, v46
	v_lshlrev_b32_e32 v46, 16, v47
	v_and_b32_e32 v47, 0xffff0000, v47
	v_pk_add_f32 v[40:41], v[26:27], v[26:27] op_sel:[0,1] op_sel_hi:[1,0]
	v_mul_f32_e32 v26, v47, v47
	v_lshlrev_b32_e32 v67, 16, v51
	v_lshlrev_b32_e32 v66, 16, v50
	v_and_b32_e32 v51, 0xffff0000, v51
	v_and_b32_e32 v50, 0xffff0000, v50
	v_pk_fma_f32 v[60:61], v[46:47], v[46:47], v[26:27] op_sel_hi:[1,1,0]
	v_pk_mul_f32 v[26:27], v[50:51], v[50:51]
	v_lshlrev_b32_e32 v71, 16, v37
	v_pk_fma_f32 v[26:27], v[66:67], v[66:67], v[26:27]
	v_lshlrev_b32_e32 v70, 16, v36
	v_and_b32_e32 v37, 0xffff0000, v37
	v_and_b32_e32 v36, 0xffff0000, v36
	v_pk_add_f32 v[68:69], v[26:27], v[26:27] op_sel:[0,1] op_sel_hi:[1,0]
	v_pk_mul_f32 v[26:27], v[36:37], v[36:37]
	v_and_b32_e32 v75, 0xffff0000, v32
	v_pk_fma_f32 v[26:27], v[70:71], v[70:71], v[26:27]
	v_lshlrev_b32_e32 v74, 16, v32
	v_pk_add_f32 v[72:73], v[26:27], v[26:27] op_sel:[0,1] op_sel_hi:[1,0]
	v_mul_f32_e32 v26, v75, v75
	v_lshlrev_b32_e32 v32, 16, v33
	v_and_b32_e32 v33, 0xffff0000, v33
	v_pk_fma_f32 v[76:77], v[74:75], v[74:75], v[26:27] op_sel_hi:[1,1,0]
	v_mul_f32_e32 v26, v33, v33
	v_and_b32_e32 v31, 0xffff0000, v43
	v_pk_fma_f32 v[78:79], v[32:33], v[32:33], v[26:27] op_sel_hi:[1,1,0]
	v_lshlrev_b32_e32 v80, 16, v24
	v_and_b32_e32 v83, 0xffff0000, v24
	v_and_b32_e32 v82, s0, v24
	v_lshlrev_b32_e32 v84, 16, v25
	v_and_b32_e32 v85, 0xffff0000, v25
	global_load_dwordx4 v[24:27], v[12:13], off
	v_lshlrev_b32_e32 v30, 16, v43
	v_and_b32_e32 v65, 0xffff0000, v48
	v_mov_b32_e32 v88, v29
	v_mov_b32_e32 v89, v31
	v_mov_b32_e32 v43, v45
	v_lshlrev_b32_e32 v62, 16, v48
	v_and_b32_e32 v64, s0, v48
	v_mov_b32_e32 v63, v65
	v_mov_b32_e32 v86, v28
	v_mov_b32_e32 v87, v30
	v_pk_mul_f32 v[88:89], v[88:89], v[88:89]
	v_pk_mul_f32 v[44:45], v[44:45], v[44:45]
	v_lshlrev_b32_e32 v48, 16, v49
	v_and_b32_e32 v49, 0xffff0000, v49
	v_pk_fma_f32 v[86:87], v[86:87], v[86:87], v[88:89]
	v_pk_mul_f32 v[64:65], v[64:65], v[64:65]
	v_pk_mov_b32 v[44:45], v[44:45], v[62:63] op_sel:[1,0]
	v_pk_add_f32 v[86:87], v[86:87], v[86:87] op_sel:[0,1] op_sel_hi:[1,0]
	v_pk_mul_f32 v[88:89], v[48:49], v[48:49]
	v_mov_b32_e32 v61, v65
	v_pk_fma_f32 v[64:65], v[42:43], v[42:43], v[44:45]
	v_pk_mul_f32 v[44:45], v[62:63], v[44:45] op_sel_hi:[0,1]
	v_mov_b32_e32 v87, v88
	v_mov_b32_e32 v41, v89
	v_mov_b32_e32 v65, v45
	v_pk_add_f32 v[40:41], v[86:87], v[40:41]
	v_pk_add_f32 v[44:45], v[64:65], v[60:61]
	v_pk_mul_f32 v[60:61], v[82:83], v[82:83]
	v_pk_add_f32 v[40:41], v[44:45], v[40:41]
	v_pk_mul_f32 v[44:45], v[84:85], v[84:85]
	v_pk_add_f32 v[40:41], v[40:41], v[40:41] op_sel:[0,1] op_sel_hi:[1,0]
	v_mov_b32_e32 v77, v44
	v_pk_add_f32 v[40:41], v[40:41], v[68:69]
	v_mov_b32_e32 v79, v45
	v_mov_b32_e32 v73, v61
	v_mul_f32_e32 v41, v80, v80
	v_pk_add_f32 v[44:45], v[76:77], v[78:79]
	v_pk_add_f32 v[40:41], v[40:41], v[72:73]
	v_mov_b32_e32 v81, v83
	v_pk_add_f32 v[40:41], v[40:41], v[44:45]
	s_nop 0
	v_add_f32_e32 v40, v40, v41
	s_nop 1
	v_add_f32_dpp v40, v40, v40 quad_perm:[1,0,3,2] row_mask:0xf bank_mask:0xf
	s_nop 1
	v_add_f32_dpp v40, v40, v40 quad_perm:[2,3,0,1] row_mask:0xf bank_mask:0xf
	s_nop 1
	v_add_f32_dpp v40, v40, v40 row_half_mirror row_mask:0xf bank_mask:0xf
	s_nop 1
	v_add_f32_dpp v40, v40, v40 row_mirror row_mask:0xf bank_mask:0xf
	ds_bpermute_b32 v41, v56, v40
	s_waitcnt lgkmcnt(0)
; #define GAS __attribute__((address_space(1)))
; __device__ __forceinline__ unsigned pk2(float lo, float hi) { f32x2_t v = {lo, hi}; bf16x2_t b = __builtin_convertvector(v, bf16x2_t); return __builtin_bit_cast(unsigned, b); }
; __device__ __forceinline__ float wave_sum(float v) {
; #pragma unroll
;     for (int o = 1; o < 64; o <<= 1) v += __shfl_xor(v, o);
;     return v;
; }
; template <bool XIN_BF, bool XOUT_BF>
; __device__ __forceinline__ void rows_update_g(const Ctx& C, const float* xin, const bf16* xin_bf, const bf16* Y, const float* wpost, float scale, float* xout, bf16* xout_bf, const float* wpre, bf16* HN) {
;     ...
;         if (wpre) { const float r2 = 1.0f / sqrtf(wave_sum(s2) * (1.0f / D) + EPS);
;             GAS v2u* o = (GAS v2u*)(HN + (size_t)m * D) + C.lane;
; #pragma unroll
;             for (int j = 0; j < 8; ++j) { const f32x4 ww = *((const GAS f32x4*)wpre + C.lane + 64 * j); o[64 * j] = (v2u){pk2(v[j].x * r2 * ww.x, v[j].y * r2 * ww.y), pk2(v[j].z * r2 * ww.z, v[j].w * r2 * ww.w)}; } }
	v_add_f32_e32 v40, v40, v41
	v_mov_b32_e32 v41, v40
	s_nop 1
	v_permlane32_swap_b32_e32 v41, v40
	v_add_f32_e32 v40, v40, v41
	v_fmamk_f32 v40, v40, 0x3a000000, v58
	v_mul_f32_e32 v41, 0x4f800000, v40
	v_cmp_gt_f32_e32 vcc, s3, v40
	s_nop 1
	v_cndmask_b32_e32 v40, v40, v41, vcc
	v_sqrt_f32_e32 v41, v40
	s_nop 0
	v_add_u32_e32 v44, -1, v41
	v_fma_f32 v45, -v44, v41, v40
	v_cmp_ge_f32_e64 s[6:7], 0, v45
	v_add_u32_e32 v45, 1, v41
	s_nop 0
	v_cndmask_b32_e64 v44, v41, v44, s[6:7]
	v_fma_f32 v41, -v45, v41, v40
	v_cmp_lt_f32_e64 s[6:7], 0, v41
	s_nop 1
	v_cndmask_b32_e64 v41, v44, v45, s[6:7]
	v_mul_f32_e32 v44, 0x37800000, v41
	v_cndmask_b32_e32 v41, v41, v44, vcc
	v_cmp_class_f32_e32 vcc, v40, v59
	s_nop 1
	v_cndmask_b32_e32 v40, v41, v40, vcc
	v_div_scale_f32 v41, s[6:7], v40, v40, 1.0
	v_rcp_f32_e32 v44, v41
	s_nop 0
	v_fma_f32 v45, -v41, v44, 1.0
	v_fmac_f32_e32 v44, v45, v44
	v_div_scale_f32 v45, vcc, 1.0, v40, 1.0
	v_mul_f32_e32 v60, v45, v44
	v_fma_f32 v61, -v41, v60, v45
	v_fmac_f32_e32 v60, v61, v44
	v_fma_f32 v41, -v41, v60, v45
	v_div_fmas_f32 v41, v41, v44, v60
	v_div_fixup_f32 v40, v41, v40, 1.0
	v_pk_mul_f32 v[28:29], v[40:41], v[28:29] op_sel_hi:[0,1]
	s_waitcnt vmcnt(0)
	v_pk_mul_f32 v[24:25], v[24:25], v[28:29]
	v_pk_mul_f32 v[28:29], v[40:41], v[30:31] op_sel_hi:[0,1]
	v_pk_mul_f32 v[26:27], v[26:27], v[28:29]
	v_cvt_pk_bf16_f32 v24, v24, v25
	v_cvt_pk_bf16_f32 v25, v26, v27
	v_add_co_u32_e32 v26, vcc, s13, v22
	v_mov_b32_e32 v28, v34
	s_nop 0
	v_addc_co_u32_e32 v27, vcc, 0, v23, vcc
	global_store_dwordx2 v[26:27], v[24:25], off
	global_load_dwordx4 v[22:25], v[12:13], off offset:1024
	v_mov_b32_e32 v29, v38
	v_mov_b32_e32 v38, v35
	v_pk_mul_f32 v[28:29], v[40:41], v[28:29] op_sel_hi:[0,1]
	v_pk_mul_f32 v[30:31], v[40:41], v[38:39] op_sel_hi:[0,1]
	s_waitcnt vmcnt(0)
	v_pk_mul_f32 v[22:23], v[22:23], v[28:29]
	v_pk_mul_f32 v[24:25], v[24:25], v[30:31]
	v_cvt_pk_bf16_f32 v22, v22, v23
	v_cvt_pk_bf16_f32 v23, v24, v25
	global_store_dwordx2 v[26:27], v[22:23], off offset:512
	global_load_dwordx4 v[22:25], v[12:13], off offset:2048
	v_pk_mul_f32 v[28:29], v[40:41], v[42:43] op_sel_hi:[0,1]
	v_pk_mul_f32 v[30:31], v[40:41], v[46:47] op_sel_hi:[0,1]
	s_waitcnt vmcnt(0)
	v_pk_mul_f32 v[22:23], v[22:23], v[28:29]
	v_pk_mul_f32 v[24:25], v[24:25], v[30:31]
	v_cvt_pk_bf16_f32 v22, v22, v23
	v_cvt_pk_bf16_f32 v23, v24, v25
	global_store_dwordx2 v[26:27], v[22:23], off offset:1024
	global_load_dwordx4 v[22:25], v[12:13], off offset:3072
	v_pk_mul_f32 v[28:29], v[40:41], v[62:63] op_sel_hi:[0,1]
	v_pk_mul_f32 v[30:31], v[40:41], v[48:49] op_sel_hi:[0,1]
	s_waitcnt vmcnt(0)
	v_pk_mul_f32 v[22:23], v[28:29], v[22:23]
	v_pk_mul_f32 v[24:25], v[30:31], v[24:25]
	v_cvt_pk_bf16_f32 v22, v22, v23
	v_cvt_pk_bf16_f32 v23, v24, v25
	global_store_dwordx2 v[26:27], v[22:23], off offset:1536
	global_load_dwordx4 v[22:25], v[14:15], off
	v_mov_b32_e32 v28, v66
	v_mov_b32_e32 v29, v50
	v_mov_b32_e32 v50, v67
	v_pk_mul_f32 v[28:29], v[40:41], v[28:29] op_sel_hi:[0,1]
	v_pk_mul_f32 v[30:31], v[40:41], v[50:51] op_sel_hi:[0,1]
	s_waitcnt vmcnt(0)
	v_pk_mul_f32 v[22:23], v[28:29], v[22:23]
	v_pk_mul_f32 v[24:25], v[30:31], v[24:25]
	v_cvt_pk_bf16_f32 v22, v22, v23
	v_cvt_pk_bf16_f32 v23, v24, v25
	global_store_dwordx2 v[26:27], v[22:23], off offset:2048
	global_load_dwordx4 v[22:25], v[16:17], off
	v_mov_b32_e32 v28, v70
	v_mov_b32_e32 v29, v36
	v_mov_b32_e32 v36, v71
	v_pk_mul_f32 v[28:29], v[40:41], v[28:29] op_sel_hi:[0,1]
	v_pk_mul_f32 v[30:31], v[40:41], v[36:37] op_sel_hi:[0,1]
	s_waitcnt vmcnt(0)
	v_pk_mul_f32 v[22:23], v[28:29], v[22:23]
	v_pk_mul_f32 v[24:25], v[30:31], v[24:25]
	v_cvt_pk_bf16_f32 v22, v22, v23
	v_cvt_pk_bf16_f32 v23, v24, v25
	global_store_dwordx2 v[26:27], v[22:23], off offset:2560
	global_load_dwordx4 v[22:25], v[18:19], off
	v_pk_mul_f32 v[28:29], v[40:41], v[74:75] op_sel_hi:[0,1]
	v_pk_mul_f32 v[30:31], v[40:41], v[32:33] op_sel_hi:[0,1]
	s_waitcnt vmcnt(0)
	v_pk_mul_f32 v[22:23], v[28:29], v[22:23]
	v_pk_mul_f32 v[24:25], v[30:31], v[24:25]
	v_cvt_pk_bf16_f32 v22, v22, v23
	v_cvt_pk_bf16_f32 v23, v24, v25
	global_store_dwordx2 v[26:27], v[22:23], off offset:3072
	global_load_dwordx4 v[22:25], v[20:21], off
	v_pk_mul_f32 v[28:29], v[40:41], v[80:81] op_sel_hi:[0,1]
	v_pk_mul_f32 v[30:31], v[40:41], v[84:85] op_sel_hi:[0,1]
	s_waitcnt vmcnt(0)
	v_pk_mul_f32 v[22:23], v[28:29], v[22:23]
	v_pk_mul_f32 v[24:25], v[30:31], v[24:25]
	v_cvt_pk_bf16_f32 v22, v22, v23
	v_cvt_pk_bf16_f32 v23, v24, v25
	global_store_dwordx2 v[26:27], v[22:23], off offset:3584
	s_branch .LBB0_1074
